# GEMM-2/3 chunk rotation now also varies with XCD-local block index (tile>>3) so blocks within one XCD read different weight chunks
# speedup vs baseline: 1.0007x; 1.0007x over previous
.Lg2_entry:
	v_and_b32_e32 v200, 63, v208
	v_lshrrev_b32_e32 v201, 6, v208
	v_lshrrev_b32_e32 v202, 3, v200
	v_and_b32_e32 v203, 7, v200
	v_xor_b32_e32 v203, v203, v202
	v_lshlrev_b32_e32 v203, 4, v203
	v_lshl_add_u32 v204, v201, 5, v202
	v_lshl_add_u32 v234, v204, 11, v203
	v_add_u32_e32 v235, 0x4000, v234
	v_add_u32_e32 v236, 0x8000, v234
	v_add_u32_e32 v237, 0xc000, v234
	v_lshlrev_b32_e32 v238, 4, v200
	v_add_u32_e32 v239, 0x8000, v238
	v_add_u32_e32 v240, 0x10000, v238
	v_add_u32_e32 v241, 0x18000, v238
	v_readfirstlane_b32 s8, v201
	s_lshl_b32 s60, s8, 12
	v_and_b32_e32 v200, 63, v208
	v_and_b32_e32 v205, 15, v200
	v_lshrrev_b32_e32 v206, 4, v200
	v_and_b32_e32 v207, 7, v205
	v_xor_b32_e32 v207, v207, v206
	v_lshlrev_b32_e32 v207, 4, v207
	v_lshl_add_u32 v242, v205, 7, v207
	v_xor_b32_e32 v243, 64, v242
	v_mov_b32_e32 v246, 0
	v_mov_b32_e32 v247, 0
	v_mov_b32_e32 v248, 0
	v_mov_b32_e32 v249, 0
	v_mov_b32_e32 v250, 0
	v_mov_b32_e32 v251, 0
	v_mov_b32_e32 v252, 0
	v_mov_b32_e32 v253, 0
	v_readlane_b32 s62, v254, 0
	v_readlane_b32 s63, v254, 1
	s_mov_b32 s21, 0
	s_lshl_b32 s8, s20, 18
	s_add_u32 s52, s92, s8
	s_addc_u32 s53, s93, 0
	s_add_i32 s8, s21, s20
	s_lshr_b32 s24, s20, 3
	s_add_i32 s8, s8, s24
	s_and_b32 s8, s8, 3
	s_lshl_b32 s8, s8, 19
	s_lshl_b32 s24, s60, 5
	s_add_i32 s8, s8, s24
	s_add_i32 s8, s8, 0x34600000
	s_add_u32 s54, s92, s8
	s_addc_u32 s55, s93, 0
	s_mov_b32 s59, 0
	s_mov_b32 s57, 0
	s_add_i32 m0, s57, s60
	s_nop 0
	global_load_lds_dwordx4 v234, s[52:53]
	s_add_i32 m0, m0, 0x400
	s_nop 0
	global_load_lds_dwordx4 v235, s[52:53]
	s_add_i32 m0, m0, 0x400
	s_nop 0
	global_load_lds_dwordx4 v236, s[52:53]
	s_add_i32 m0, m0, 0x400
	s_nop 0
	global_load_lds_dwordx4 v237, s[52:53]
	s_add_u32 s52, s52, 128
	s_addc_u32 s53, s53, 0
	global_load_dwordx4 v[128:131], v238, s[54:55]
	global_load_dwordx4 v[132:135], v239, s[54:55]
	global_load_dwordx4 v[136:139], v240, s[54:55]
	global_load_dwordx4 v[140:143], v241, s[54:55]
	s_add_u32 s54, s54, 1024
	s_addc_u32 s55, s55, 0
	s_add_i32 s59, s59, 1
	global_load_dwordx4 v[144:147], v238, s[54:55]
	global_load_dwordx4 v[148:151], v239, s[54:55]
	global_load_dwordx4 v[152:155], v240, s[54:55]
	global_load_dwordx4 v[156:159], v241, s[54:55]
	s_add_u32 s54, s54, 1024
	s_addc_u32 s55, s55, 0
	s_add_i32 s59, s59, 1
	s_movk_i32 s57, 0x4000
	s_add_i32 m0, s57, s60
	s_nop 0
	global_load_lds_dwordx4 v234, s[52:53]
	s_add_i32 m0, m0, 0x400
	s_nop 0
	global_load_lds_dwordx4 v235, s[52:53]
	s_add_i32 m0, m0, 0x400
	s_nop 0
	global_load_lds_dwordx4 v236, s[52:53]
	s_add_i32 m0, m0, 0x400
	s_nop 0
	global_load_lds_dwordx4 v237, s[52:53]
	s_add_u32 s52, s52, 128
	s_addc_u32 s53, s53, 0
	global_load_dwordx4 v[160:163], v238, s[54:55]
	global_load_dwordx4 v[164:167], v239, s[54:55]
	global_load_dwordx4 v[168:171], v240, s[54:55]
	global_load_dwordx4 v[172:175], v241, s[54:55]
	s_add_u32 s54, s54, 1024
	s_addc_u32 s55, s55, 0
	s_add_i32 s59, s59, 1
	s_mov_b32 s56, 0
	s_mov_b32 s57, 0x8000

.Lg2_sww0:
	s_cmp_lt_u32 s21, 3
	s_cbranch_scc0 .Lg2_wndw0
	s_add_i32 s25, s21, 1
	s_add_i32 s8, s25, s20
	s_lshr_b32 s24, s20, 3
	s_add_i32 s8, s8, s24
	s_and_b32 s8, s8, 3
	s_lshl_b32 s8, s8, 19
	s_lshl_b32 s24, s60, 5
	s_add_i32 s8, s8, s24
	s_add_i32 s8, s8, 0x34600000
	s_add_u32 s54, s92, s8
	s_addc_u32 s55, s93, 0

.Lg2_wndw5:
.Lg2_swdw5:
	s_add_i32 s59, s59, 1
	ds_read_b128 v[200:203], v245 offset:0
	ds_read_b128 v[204:207], v245 offset:2048
	ds_read_b128 v[210:213], v245 offset:4096
	ds_read_b128 v[214:217], v245 offset:6144
	ds_read_b128 v[218:221], v245 offset:8192
	ds_read_b128 v[222:225], v245 offset:10240
	ds_read_b128 v[226:229], v245 offset:12288
	ds_read_b128 v[230:233], v245 offset:14336
	s_waitcnt lgkmcnt(4)
	v_mfma_f32_16x16x32_bf16 v[0:3], v[176:179], v[200:203], v[0:3]
	v_mfma_f32_16x16x32_bf16 v[32:35], v[184:187], v[200:203], v[32:35]
	v_mfma_f32_16x16x32_bf16 v[64:67], v[188:191], v[200:203], v[64:67]
	v_mfma_f32_16x16x32_bf16 v[96:99], v[196:199], v[200:203], v[96:99]
	v_mfma_f32_16x16x32_bf16 v[4:7], v[176:179], v[204:207], v[4:7]
	v_mfma_f32_16x16x32_bf16 v[36:39], v[184:187], v[204:207], v[36:39]
	v_mfma_f32_16x16x32_bf16 v[68:71], v[188:191], v[204:207], v[68:71]
	v_mfma_f32_16x16x32_bf16 v[100:103], v[196:199], v[204:207], v[100:103]
	v_mfma_f32_16x16x32_bf16 v[8:11], v[176:179], v[210:213], v[8:11]
	v_mfma_f32_16x16x32_bf16 v[40:43], v[184:187], v[210:213], v[40:43]
	v_mfma_f32_16x16x32_bf16 v[72:75], v[188:191], v[210:213], v[72:75]
	v_mfma_f32_16x16x32_bf16 v[104:107], v[196:199], v[210:213], v[104:107]
	v_mfma_f32_16x16x32_bf16 v[12:15], v[176:179], v[214:217], v[12:15]
	v_mfma_f32_16x16x32_bf16 v[44:47], v[184:187], v[214:217], v[44:47]
	v_mfma_f32_16x16x32_bf16 v[76:79], v[188:191], v[214:217], v[76:79]
	v_mfma_f32_16x16x32_bf16 v[108:111], v[196:199], v[214:217], v[108:111]
	s_waitcnt lgkmcnt(0)
	v_mfma_f32_16x16x32_bf16 v[16:19], v[176:179], v[218:221], v[16:19]
	v_mfma_f32_16x16x32_bf16 v[48:51], v[184:187], v[218:221], v[48:51]
	v_mfma_f32_16x16x32_bf16 v[80:83], v[188:191], v[218:221], v[80:83]
	v_mfma_f32_16x16x32_bf16 v[112:115], v[196:199], v[218:221], v[112:115]
	v_mfma_f32_16x16x32_bf16 v[20:23], v[176:179], v[222:225], v[20:23]
	v_mfma_f32_16x16x32_bf16 v[52:55], v[184:187], v[222:225], v[52:55]
	v_mfma_f32_16x16x32_bf16 v[84:87], v[188:191], v[222:225], v[84:87]
	v_mfma_f32_16x16x32_bf16 v[116:119], v[196:199], v[222:225], v[116:119]
	v_mfma_f32_16x16x32_bf16 v[24:27], v[176:179], v[226:229], v[24:27]
	v_mfma_f32_16x16x32_bf16 v[56:59], v[184:187], v[226:229], v[56:59]
	v_mfma_f32_16x16x32_bf16 v[88:91], v[188:191], v[226:229], v[88:91]
	v_mfma_f32_16x16x32_bf16 v[120:123], v[196:199], v[226:229], v[120:123]
	v_mfma_f32_16x16x32_bf16 v[28:31], v[176:179], v[230:233], v[28:31]
	v_mfma_f32_16x16x32_bf16 v[60:63], v[184:187], v[230:233], v[60:63]
	v_mfma_f32_16x16x32_bf16 v[92:95], v[188:191], v[230:233], v[92:95]
	v_mfma_f32_16x16x32_bf16 v[124:127], v[196:199], v[230:233], v[124:127]
	s_add_i32 s56, s56, 0x4000
	s_cmp_lt_u32 s56, 0xc000
	s_cselect_b32 s56, s56, 0
	s_add_i32 s57, s57, 0x4000
	s_cmp_lt_u32 s57, 0xc000
	s_cselect_b32 s57, s57, 0
	s_add_i32 s58, s58, 1
	s_cmp_lt_u32 s58, 16
	s_cbranch_scc1 .Lg2_loop
	s_nop 7
	s_nop 7
	v_and_b32_e32 v200, 63, v208
	v_lshrrev_b32_e32 v201, 6, v208
	v_and_b32_e32 v202, 15, v200
	v_lshrrev_b32_e32 v203, 4, v200
	s_add_i32 s24, s21, s20
	s_lshr_b32 s8, s20, 3
	s_add_i32 s24, s24, s8
	s_and_b32 s24, s24, 3
	s_lshl_b32 s24, s24, 8
	s_lshl_b32 s8, s20, 7
	v_add_u32_e32 v204, s8, v202
	v_lshlrev_b32_e32 v205, 2, v203
	v_lshl_add_u32 v205, v201, 6, v205
	v_add_u32_e32 v205, s24, v205
	v_lshlrev_b32_e32 v206, 12, v204
	v_lshl_add_u32 v206, v205, 2, v206
	v_mov_b32_e32 v245, s63
	v_add_co_u32_e32 v244, vcc, s62, v206
	s_nop 1
	v_addc_co_u32_e32 v245, vcc, 0, v245, vcc
	v_lshlrev_b32_e32 v206, 11, v204
	v_lshl_add_u32 v206, v205, 1, v206
	v_add_u32_e32 v206, 0x1e000000, v206
	v_mov_b32_e32 v243, s93
	v_add_co_u32_e32 v242, vcc, s92, v206
	s_nop 1
	v_addc_co_u32_e32 v243, vcc, 0, v243, vcc
	global_load_dwordx4 v[200:203], v[244:245], off offset:0
	global_load_dwordx4 v[204:207], v[244:245], off offset:64
	global_load_dwordx4 v[210:213], v[244:245], off offset:128
	global_load_dwordx4 v[214:217], v[244:245], off offset:192
	v_add_co_u32_e32 v244, vcc, 0x10000, v244
	s_nop 1
	v_addc_co_u32_e32 v245, vcc, 0, v245, vcc
	global_load_dwordx4 v[218:221], v[244:245], off offset:0
	global_load_dwordx4 v[222:225], v[244:245], off offset:64
	global_load_dwordx4 v[226:229], v[244:245], off offset:128
	global_load_dwordx4 v[230:233], v[244:245], off offset:192
	v_add_co_u32_e32 v244, vcc, 0x10000, v244
	s_nop 1
	v_addc_co_u32_e32 v245, vcc, 0, v245, vcc
	s_waitcnt vmcnt(4)
	v_pk_add_f32 v[200:201], v[200:201], v[0:1]
	v_pk_add_f32 v[202:203], v[202:203], v[2:3]
	v_fmac_f32_e32 v246, v200, v200
	v_fmac_f32_e32 v246, v201, v201
	v_fmac_f32_e32 v246, v202, v202
	v_fmac_f32_e32 v246, v203, v203
	v_cvt_pk_bf16_f32 v200, v200, v201
	v_cvt_pk_bf16_f32 v201, v202, v203
	global_store_dwordx2 v[242:243], v[200:201], off offset:0
	v_pk_add_f32 v[204:205], v[204:205], v[32:33]
	v_pk_add_f32 v[206:207], v[206:207], v[34:35]
	v_fmac_f32_e32 v246, v204, v204
	v_fmac_f32_e32 v246, v205, v205
	v_fmac_f32_e32 v246, v206, v206
	v_fmac_f32_e32 v246, v207, v207
	v_cvt_pk_bf16_f32 v204, v204, v205
	v_cvt_pk_bf16_f32 v205, v206, v207
	global_store_dwordx2 v[242:243], v[204:205], off offset:32
	v_pk_add_f32 v[210:211], v[210:211], v[64:65]
	v_pk_add_f32 v[212:213], v[212:213], v[66:67]
	v_fmac_f32_e32 v246, v210, v210
	v_fmac_f32_e32 v246, v211, v211
	v_fmac_f32_e32 v246, v212, v212
	v_fmac_f32_e32 v246, v213, v213
	v_cvt_pk_bf16_f32 v210, v210, v211
	v_cvt_pk_bf16_f32 v211, v212, v213
	global_store_dwordx2 v[242:243], v[210:211], off offset:64
	v_pk_add_f32 v[214:215], v[214:215], v[96:97]
	v_pk_add_f32 v[216:217], v[216:217], v[98:99]
	v_fmac_f32_e32 v246, v214, v214
	v_fmac_f32_e32 v246, v215, v215
	v_fmac_f32_e32 v246, v216, v216
	v_fmac_f32_e32 v246, v217, v217
	v_cvt_pk_bf16_f32 v214, v214, v215
	v_cvt_pk_bf16_f32 v215, v216, v217
	global_store_dwordx2 v[242:243], v[214:215], off offset:96
	v_add_co_u32_e32 v242, vcc, 0x8000, v242
	s_nop 1
	v_addc_co_u32_e32 v243, vcc, 0, v243, vcc
	global_load_dwordx4 v[200:203], v[244:245], off offset:0
	global_load_dwordx4 v[204:207], v[244:245], off offset:64
	global_load_dwordx4 v[210:213], v[244:245], off offset:128
	global_load_dwordx4 v[214:217], v[244:245], off offset:192
	v_add_co_u32_e32 v244, vcc, 0x10000, v244
	s_nop 1
	v_addc_co_u32_e32 v245, vcc, 0, v245, vcc
	s_waitcnt vmcnt(8)
	v_pk_add_f32 v[218:219], v[218:219], v[4:5]
	v_pk_add_f32 v[220:221], v[220:221], v[6:7]
	v_fmac_f32_e32 v247, v218, v218
	v_fmac_f32_e32 v247, v219, v219
	v_fmac_f32_e32 v247, v220, v220
	v_fmac_f32_e32 v247, v221, v221
	v_cvt_pk_bf16_f32 v218, v218, v219
	v_cvt_pk_bf16_f32 v219, v220, v221
	global_store_dwordx2 v[242:243], v[218:219], off offset:0
	v_pk_add_f32 v[222:223], v[222:223], v[36:37]
	v_pk_add_f32 v[224:225], v[224:225], v[38:39]
	v_fmac_f32_e32 v247, v222, v222
	v_fmac_f32_e32 v247, v223, v223
	v_fmac_f32_e32 v247, v224, v224
	v_fmac_f32_e32 v247, v225, v225
	v_cvt_pk_bf16_f32 v222, v222, v223
	v_cvt_pk_bf16_f32 v223, v224, v225
	global_store_dwordx2 v[242:243], v[222:223], off offset:32
	v_pk_add_f32 v[226:227], v[226:227], v[68:69]
	v_pk_add_f32 v[228:229], v[228:229], v[70:71]
	v_fmac_f32_e32 v247, v226, v226
	v_fmac_f32_e32 v247, v227, v227
	v_fmac_f32_e32 v247, v228, v228
	v_fmac_f32_e32 v247, v229, v229
	v_cvt_pk_bf16_f32 v226, v226, v227
	v_cvt_pk_bf16_f32 v227, v228, v229
	global_store_dwordx2 v[242:243], v[226:227], off offset:64
	v_pk_add_f32 v[230:231], v[230:231], v[100:101]
	v_pk_add_f32 v[232:233], v[232:233], v[102:103]
	v_fmac_f32_e32 v247, v230, v230
	v_fmac_f32_e32 v247, v231, v231
	v_fmac_f32_e32 v247, v232, v232
	v_fmac_f32_e32 v247, v233, v233
	v_cvt_pk_bf16_f32 v230, v230, v231
	v_cvt_pk_bf16_f32 v231, v232, v233
	global_store_dwordx2 v[242:243], v[230:231], off offset:96
	v_add_co_u32_e32 v242, vcc, 0x8000, v242
	s_nop 1
	v_addc_co_u32_e32 v243, vcc, 0, v243, vcc
	global_load_dwordx4 v[218:221], v[244:245], off offset:0
	global_load_dwordx4 v[222:225], v[244:245], off offset:64
	global_load_dwordx4 v[226:229], v[244:245], off offset:128
	global_load_dwordx4 v[230:233], v[244:245], off offset:192
	v_add_co_u32_e32 v244, vcc, 0x10000, v244
	s_nop 1
	v_addc_co_u32_e32 v245, vcc, 0, v245, vcc
	s_waitcnt vmcnt(8)
	v_pk_add_f32 v[200:201], v[200:201], v[8:9]
	v_pk_add_f32 v[202:203], v[202:203], v[10:11]
	v_fmac_f32_e32 v248, v200, v200
	v_fmac_f32_e32 v248, v201, v201
	v_fmac_f32_e32 v248, v202, v202
	v_fmac_f32_e32 v248, v203, v203
	v_cvt_pk_bf16_f32 v200, v200, v201
	v_cvt_pk_bf16_f32 v201, v202, v203
	global_store_dwordx2 v[242:243], v[200:201], off offset:0
	v_pk_add_f32 v[204:205], v[204:205], v[40:41]
	v_pk_add_f32 v[206:207], v[206:207], v[42:43]
	v_fmac_f32_e32 v248, v204, v204
	v_fmac_f32_e32 v248, v205, v205
	v_fmac_f32_e32 v248, v206, v206
	v_fmac_f32_e32 v248, v207, v207
	v_cvt_pk_bf16_f32 v204, v204, v205
	v_cvt_pk_bf16_f32 v205, v206, v207
	global_store_dwordx2 v[242:243], v[204:205], off offset:32
	v_pk_add_f32 v[210:211], v[210:211], v[72:73]
	v_pk_add_f32 v[212:213], v[212:213], v[74:75]
	v_fmac_f32_e32 v248, v210, v210
	v_fmac_f32_e32 v248, v211, v211
	v_fmac_f32_e32 v248, v212, v212
	v_fmac_f32_e32 v248, v213, v213
	v_cvt_pk_bf16_f32 v210, v210, v211
	v_cvt_pk_bf16_f32 v211, v212, v213
	global_store_dwordx2 v[242:243], v[210:211], off offset:64
	v_pk_add_f32 v[214:215], v[214:215], v[104:105]
	v_pk_add_f32 v[216:217], v[216:217], v[106:107]
	v_fmac_f32_e32 v248, v214, v214
	v_fmac_f32_e32 v248, v215, v215
	v_fmac_f32_e32 v248, v216, v216
	v_fmac_f32_e32 v248, v217, v217
	v_cvt_pk_bf16_f32 v214, v214, v215
	v_cvt_pk_bf16_f32 v215, v216, v217
	global_store_dwordx2 v[242:243], v[214:215], off offset:96
	v_add_co_u32_e32 v242, vcc, 0x8000, v242
	s_nop 1
	v_addc_co_u32_e32 v243, vcc, 0, v243, vcc
	global_load_dwordx4 v[200:203], v[244:245], off offset:0
	global_load_dwordx4 v[204:207], v[244:245], off offset:64
	global_load_dwordx4 v[210:213], v[244:245], off offset:128
	global_load_dwordx4 v[214:217], v[244:245], off offset:192
	v_add_co_u32_e32 v244, vcc, 0x10000, v244
	s_nop 1
	v_addc_co_u32_e32 v245, vcc, 0, v245, vcc
	s_waitcnt vmcnt(8)
	v_pk_add_f32 v[218:219], v[218:219], v[12:13]
	v_pk_add_f32 v[220:221], v[220:221], v[14:15]
	v_fmac_f32_e32 v249, v218, v218
	v_fmac_f32_e32 v249, v219, v219
	v_fmac_f32_e32 v249, v220, v220
	v_fmac_f32_e32 v249, v221, v221
	v_cvt_pk_bf16_f32 v218, v218, v219
	v_cvt_pk_bf16_f32 v219, v220, v221
	global_store_dwordx2 v[242:243], v[218:219], off offset:0
	v_pk_add_f32 v[222:223], v[222:223], v[44:45]
	v_pk_add_f32 v[224:225], v[224:225], v[46:47]
	v_fmac_f32_e32 v249, v222, v222
	v_fmac_f32_e32 v249, v223, v223
	v_fmac_f32_e32 v249, v224, v224
	v_fmac_f32_e32 v249, v225, v225
	v_cvt_pk_bf16_f32 v222, v222, v223
	v_cvt_pk_bf16_f32 v223, v224, v225
	global_store_dwordx2 v[242:243], v[222:223], off offset:32
	v_pk_add_f32 v[226:227], v[226:227], v[76:77]
	v_pk_add_f32 v[228:229], v[228:229], v[78:79]
	v_fmac_f32_e32 v249, v226, v226
	v_fmac_f32_e32 v249, v227, v227
	v_fmac_f32_e32 v249, v228, v228
	v_fmac_f32_e32 v249, v229, v229
	v_cvt_pk_bf16_f32 v226, v226, v227
	v_cvt_pk_bf16_f32 v227, v228, v229
	global_store_dwordx2 v[242:243], v[226:227], off offset:64
	v_pk_add_f32 v[230:231], v[230:231], v[108:109]
	v_pk_add_f32 v[232:233], v[232:233], v[110:111]
	v_fmac_f32_e32 v249, v230, v230
	v_fmac_f32_e32 v249, v231, v231
	v_fmac_f32_e32 v249, v232, v232
	v_fmac_f32_e32 v249, v233, v233
	v_cvt_pk_bf16_f32 v230, v230, v231
	v_cvt_pk_bf16_f32 v231, v232, v233
	global_store_dwordx2 v[242:243], v[230:231], off offset:96
	v_add_co_u32_e32 v242, vcc, 0x8000, v242
	s_nop 1
	v_addc_co_u32_e32 v243, vcc, 0, v243, vcc
	global_load_dwordx4 v[218:221], v[244:245], off offset:0
	global_load_dwordx4 v[222:225], v[244:245], off offset:64
	global_load_dwordx4 v[226:229], v[244:245], off offset:128
	global_load_dwordx4 v[230:233], v[244:245], off offset:192
	v_add_co_u32_e32 v244, vcc, 0x10000, v244
	s_nop 1
	v_addc_co_u32_e32 v245, vcc, 0, v245, vcc
	s_waitcnt vmcnt(8)
	v_pk_add_f32 v[200:201], v[200:201], v[16:17]
	v_pk_add_f32 v[202:203], v[202:203], v[18:19]
	v_fmac_f32_e32 v250, v200, v200
	v_fmac_f32_e32 v250, v201, v201
	v_fmac_f32_e32 v250, v202, v202
	v_fmac_f32_e32 v250, v203, v203
	v_cvt_pk_bf16_f32 v200, v200, v201
	v_cvt_pk_bf16_f32 v201, v202, v203
	global_store_dwordx2 v[242:243], v[200:201], off offset:0
	v_pk_add_f32 v[204:205], v[204:205], v[48:49]
	v_pk_add_f32 v[206:207], v[206:207], v[50:51]
	v_fmac_f32_e32 v250, v204, v204
	v_fmac_f32_e32 v250, v205, v205
	v_fmac_f32_e32 v250, v206, v206
	v_fmac_f32_e32 v250, v207, v207
	v_cvt_pk_bf16_f32 v204, v204, v205
	v_cvt_pk_bf16_f32 v205, v206, v207
	global_store_dwordx2 v[242:243], v[204:205], off offset:32
	v_pk_add_f32 v[210:211], v[210:211], v[80:81]
	v_pk_add_f32 v[212:213], v[212:213], v[82:83]
	v_fmac_f32_e32 v250, v210, v210
	v_fmac_f32_e32 v250, v211, v211
	v_fmac_f32_e32 v250, v212, v212
	v_fmac_f32_e32 v250, v213, v213
	v_cvt_pk_bf16_f32 v210, v210, v211
	v_cvt_pk_bf16_f32 v211, v212, v213
	global_store_dwordx2 v[242:243], v[210:211], off offset:64
	v_pk_add_f32 v[214:215], v[214:215], v[112:113]
	v_pk_add_f32 v[216:217], v[216:217], v[114:115]
	v_fmac_f32_e32 v250, v214, v214
	v_fmac_f32_e32 v250, v215, v215
	v_fmac_f32_e32 v250, v216, v216
	v_fmac_f32_e32 v250, v217, v217
	v_cvt_pk_bf16_f32 v214, v214, v215
	v_cvt_pk_bf16_f32 v215, v216, v217
	global_store_dwordx2 v[242:243], v[214:215], off offset:96
	v_add_co_u32_e32 v242, vcc, 0x8000, v242
	s_nop 1
	v_addc_co_u32_e32 v243, vcc, 0, v243, vcc
	global_load_dwordx4 v[200:203], v[244:245], off offset:0
	global_load_dwordx4 v[204:207], v[244:245], off offset:64
	global_load_dwordx4 v[210:213], v[244:245], off offset:128
	global_load_dwordx4 v[214:217], v[244:245], off offset:192
	v_add_co_u32_e32 v244, vcc, 0x10000, v244
	s_nop 1
	v_addc_co_u32_e32 v245, vcc, 0, v245, vcc
	s_waitcnt vmcnt(8)
	v_pk_add_f32 v[218:219], v[218:219], v[20:21]
	v_pk_add_f32 v[220:221], v[220:221], v[22:23]
	v_fmac_f32_e32 v251, v218, v218
	v_fmac_f32_e32 v251, v219, v219
	v_fmac_f32_e32 v251, v220, v220
	v_fmac_f32_e32 v251, v221, v221
	v_cvt_pk_bf16_f32 v218, v218, v219
	v_cvt_pk_bf16_f32 v219, v220, v221
	global_store_dwordx2 v[242:243], v[218:219], off offset:0
	v_pk_add_f32 v[222:223], v[222:223], v[52:53]
	v_pk_add_f32 v[224:225], v[224:225], v[54:55]
	v_fmac_f32_e32 v251, v222, v222
	v_fmac_f32_e32 v251, v223, v223
	v_fmac_f32_e32 v251, v224, v224
	v_fmac_f32_e32 v251, v225, v225
	v_cvt_pk_bf16_f32 v222, v222, v223
	v_cvt_pk_bf16_f32 v223, v224, v225
	global_store_dwordx2 v[242:243], v[222:223], off offset:32
	v_pk_add_f32 v[226:227], v[226:227], v[84:85]
	v_pk_add_f32 v[228:229], v[228:229], v[86:87]
	v_fmac_f32_e32 v251, v226, v226
	v_fmac_f32_e32 v251, v227, v227
	v_fmac_f32_e32 v251, v228, v228
	v_fmac_f32_e32 v251, v229, v229
	v_cvt_pk_bf16_f32 v226, v226, v227
	v_cvt_pk_bf16_f32 v227, v228, v229
	global_store_dwordx2 v[242:243], v[226:227], off offset:64
	v_pk_add_f32 v[230:231], v[230:231], v[116:117]
	v_pk_add_f32 v[232:233], v[232:233], v[118:119]
	v_fmac_f32_e32 v251, v230, v230
	v_fmac_f32_e32 v251, v231, v231
	v_fmac_f32_e32 v251, v232, v232
	v_fmac_f32_e32 v251, v233, v233
	v_cvt_pk_bf16_f32 v230, v230, v231
	v_cvt_pk_bf16_f32 v231, v232, v233
	global_store_dwordx2 v[242:243], v[230:231], off offset:96
	v_add_co_u32_e32 v242, vcc, 0x8000, v242
	s_nop 1
	v_addc_co_u32_e32 v243, vcc, 0, v243, vcc
	global_load_dwordx4 v[218:221], v[244:245], off offset:0
	global_load_dwordx4 v[222:225], v[244:245], off offset:64
	global_load_dwordx4 v[226:229], v[244:245], off offset:128
	global_load_dwordx4 v[230:233], v[244:245], off offset:192
	v_add_co_u32_e32 v244, vcc, 0x10000, v244
	s_nop 1
	v_addc_co_u32_e32 v245, vcc, 0, v245, vcc
	s_waitcnt vmcnt(8)
	v_pk_add_f32 v[200:201], v[200:201], v[24:25]
	v_pk_add_f32 v[202:203], v[202:203], v[26:27]
	v_fmac_f32_e32 v252, v200, v200
	v_fmac_f32_e32 v252, v201, v201
	v_fmac_f32_e32 v252, v202, v202
	v_fmac_f32_e32 v252, v203, v203
	v_cvt_pk_bf16_f32 v200, v200, v201
	v_cvt_pk_bf16_f32 v201, v202, v203
	global_store_dwordx2 v[242:243], v[200:201], off offset:0
	v_pk_add_f32 v[204:205], v[204:205], v[56:57]
	v_pk_add_f32 v[206:207], v[206:207], v[58:59]
	v_fmac_f32_e32 v252, v204, v204
	v_fmac_f32_e32 v252, v205, v205
	v_fmac_f32_e32 v252, v206, v206
	v_fmac_f32_e32 v252, v207, v207
	v_cvt_pk_bf16_f32 v204, v204, v205
	v_cvt_pk_bf16_f32 v205, v206, v207
	global_store_dwordx2 v[242:243], v[204:205], off offset:32
	v_pk_add_f32 v[210:211], v[210:211], v[88:89]
	v_pk_add_f32 v[212:213], v[212:213], v[90:91]
	v_fmac_f32_e32 v252, v210, v210
	v_fmac_f32_e32 v252, v211, v211
	v_fmac_f32_e32 v252, v212, v212
	v_fmac_f32_e32 v252, v213, v213
	v_cvt_pk_bf16_f32 v210, v210, v211
	v_cvt_pk_bf16_f32 v211, v212, v213
	global_store_dwordx2 v[242:243], v[210:211], off offset:64
	v_pk_add_f32 v[214:215], v[214:215], v[120:121]
	v_pk_add_f32 v[216:217], v[216:217], v[122:123]
	v_fmac_f32_e32 v252, v214, v214
	v_fmac_f32_e32 v252, v215, v215
	v_fmac_f32_e32 v252, v216, v216
	v_fmac_f32_e32 v252, v217, v217
	v_cvt_pk_bf16_f32 v214, v214, v215
	v_cvt_pk_bf16_f32 v215, v216, v217
	global_store_dwordx2 v[242:243], v[214:215], off offset:96
	v_add_co_u32_e32 v242, vcc, 0x8000, v242
	s_nop 1
	v_addc_co_u32_e32 v243, vcc, 0, v243, vcc
	s_waitcnt vmcnt(4)
	v_pk_add_f32 v[218:219], v[218:219], v[28:29]
	v_pk_add_f32 v[220:221], v[220:221], v[30:31]
	v_fmac_f32_e32 v253, v218, v218
	v_fmac_f32_e32 v253, v219, v219
	v_fmac_f32_e32 v253, v220, v220
	v_fmac_f32_e32 v253, v221, v221
	v_cvt_pk_bf16_f32 v218, v218, v219
	v_cvt_pk_bf16_f32 v219, v220, v221
	global_store_dwordx2 v[242:243], v[218:219], off offset:0
	v_pk_add_f32 v[222:223], v[222:223], v[60:61]
	v_pk_add_f32 v[224:225], v[224:225], v[62:63]
	v_fmac_f32_e32 v253, v222, v222
	v_fmac_f32_e32 v253, v223, v223
	v_fmac_f32_e32 v253, v224, v224
	v_fmac_f32_e32 v253, v225, v225
	v_cvt_pk_bf16_f32 v222, v222, v223
	v_cvt_pk_bf16_f32 v223, v224, v225
	global_store_dwordx2 v[242:243], v[222:223], off offset:32
	v_pk_add_f32 v[226:227], v[226:227], v[92:93]
	v_pk_add_f32 v[228:229], v[228:229], v[94:95]
	v_fmac_f32_e32 v253, v226, v226
	v_fmac_f32_e32 v253, v227, v227
	v_fmac_f32_e32 v253, v228, v228
	v_fmac_f32_e32 v253, v229, v229
	v_cvt_pk_bf16_f32 v226, v226, v227
	v_cvt_pk_bf16_f32 v227, v228, v229
	global_store_dwordx2 v[242:243], v[226:227], off offset:64
	v_pk_add_f32 v[230:231], v[230:231], v[124:125]
	v_pk_add_f32 v[232:233], v[232:233], v[126:127]
	v_fmac_f32_e32 v253, v230, v230
	v_fmac_f32_e32 v253, v231, v231
	v_fmac_f32_e32 v253, v232, v232
	v_fmac_f32_e32 v253, v233, v233
	v_cvt_pk_bf16_f32 v230, v230, v231
	v_cvt_pk_bf16_f32 v231, v232, v233
	global_store_dwordx2 v[242:243], v[230:231], off offset:96
	v_add_co_u32_e32 v242, vcc, 0x8000, v242
	s_nop 1
	v_addc_co_u32_e32 v243, vcc, 0, v243, vcc
	v_and_b32_e32 v200, 63, v208
	v_and_b32_e32 v205, 15, v200
	v_lshrrev_b32_e32 v206, 4, v200
	v_and_b32_e32 v207, 7, v205
	v_xor_b32_e32 v207, v207, v206
	v_lshlrev_b32_e32 v207, 4, v207
	v_lshl_add_u32 v242, v205, 7, v207
	v_xor_b32_e32 v243, 64, v242
	s_add_i32 s21, s21, 1
	s_cmp_lt_u32 s21, 4
	s_cbranch_scc1 .Lg2_chunk
	s_waitcnt vmcnt(0)
	v_and_b32_e32 v200, 63, v208
	v_xor_b32_e32 v201, 16, v200
	v_lshlrev_b32_e32 v201, 2, v201
	v_xor_b32_e32 v202, 32, v200
	v_lshlrev_b32_e32 v202, 2, v202
	v_and_b32_e32 v203, 15, v200
	v_lshlrev_b32_e32 v203, 2, v203
	v_add_u32_e32 v203, 0x12400, v203
	ds_bpermute_b32 v204, v201, v246
	s_waitcnt lgkmcnt(0)
	v_add_f32_e32 v246, v246, v204
	ds_bpermute_b32 v204, v202, v246
	s_waitcnt lgkmcnt(0)
	v_add_f32_e32 v246, v246, v204
	ds_bpermute_b32 v204, v201, v247
	s_waitcnt lgkmcnt(0)
	v_add_f32_e32 v247, v247, v204
	ds_bpermute_b32 v204, v202, v247
	s_waitcnt lgkmcnt(0)
	v_add_f32_e32 v247, v247, v204
	ds_bpermute_b32 v204, v201, v248
	s_waitcnt lgkmcnt(0)
	v_add_f32_e32 v248, v248, v204
	ds_bpermute_b32 v204, v202, v248
	s_waitcnt lgkmcnt(0)
	v_add_f32_e32 v248, v248, v204
	ds_bpermute_b32 v204, v201, v249
	s_waitcnt lgkmcnt(0)
	v_add_f32_e32 v249, v249, v204
	ds_bpermute_b32 v204, v202, v249
	s_waitcnt lgkmcnt(0)
	v_add_f32_e32 v249, v249, v204
	ds_bpermute_b32 v204, v201, v250
	s_waitcnt lgkmcnt(0)
	v_add_f32_e32 v250, v250, v204
	ds_bpermute_b32 v204, v202, v250
	s_waitcnt lgkmcnt(0)
	v_add_f32_e32 v250, v250, v204
	ds_bpermute_b32 v204, v201, v251
	s_waitcnt lgkmcnt(0)
	v_add_f32_e32 v251, v251, v204
	ds_bpermute_b32 v204, v202, v251
	s_waitcnt lgkmcnt(0)
	v_add_f32_e32 v251, v251, v204
	ds_bpermute_b32 v204, v201, v252
	s_waitcnt lgkmcnt(0)
	v_add_f32_e32 v252, v252, v204
	ds_bpermute_b32 v204, v202, v252
	s_waitcnt lgkmcnt(0)
	v_add_f32_e32 v252, v252, v204
	ds_bpermute_b32 v204, v201, v253
	s_waitcnt lgkmcnt(0)
	v_add_f32_e32 v253, v253, v204
	ds_bpermute_b32 v204, v202, v253
	s_waitcnt lgkmcnt(0)
	v_add_f32_e32 v253, v253, v204
	s_mov_b64 s[24:25], exec
	s_mov_b64 exec, 0xffff
	ds_add_f32 v203, v246 offset:0
	ds_add_f32 v203, v247 offset:64
	ds_add_f32 v203, v248 offset:128
	ds_add_f32 v203, v249 offset:192
	ds_add_f32 v203, v250 offset:256
	ds_add_f32 v203, v251 offset:320
	ds_add_f32 v203, v252 offset:384
	ds_add_f32 v203, v253 offset:448
	s_mov_b64 exec, s[24:25]


.LBB0_345:
	v_and_b32_e32 v246, 63, v208
	v_lshrrev_b32_e32 v247, 6, v208
	v_lshrrev_b32_e32 v248, 3, v246
	v_and_b32_e32 v249, 7, v246
	v_xor_b32_e32 v249, v249, v248
	v_lshlrev_b32_e32 v249, 4, v249
	v_lshl_add_u32 v250, v247, 5, v248
	v_lshl_add_u32 v234, v250, 11, v249
	v_add_u32_e32 v235, 0x4000, v234
	v_add_u32_e32 v236, 0x8000, v234
	v_add_u32_e32 v237, 0xc000, v234
	v_lshlrev_b32_e32 v238, 4, v246
	v_add_u32_e32 v239, 0x8000, v238
	v_add_u32_e32 v240, 0x10000, v238
	v_add_u32_e32 v241, 0x18000, v238
	v_readfirstlane_b32 s2, v247
	s_lshl_b32 s20, s2, 12
	v_and_b32_e32 v251, 15, v246
	v_lshrrev_b32_e32 v252, 4, v246
	v_and_b32_e32 v253, 7, v251
	v_xor_b32_e32 v253, v253, v252
	v_lshlrev_b32_e32 v253, 4, v253
	v_lshl_add_u32 v242, v251, 7, v253
	v_xor_b32_e32 v243, 64, v242
	s_mov_b32 s11, 0
	v_and_b32_e32 v244, 15, v208
	v_lshlrev_b32_e32 v244, 2, v244
	s_lshl_b32 s2, s10, 9
	s_add_i32 s2, s2, 0x36c80000
	v_add_u32_e32 v244, s2, v244
	v_mov_b32_e32 v245, s93
	v_add_co_u32_e32 v244, vcc, s92, v244
	s_nop 1
	v_addc_co_u32_e32 v245, vcc, 0, v245, vcc
	global_load_dword v246, v[244:245], off
	global_load_dword v247, v[244:245], off offset:64
	global_load_dword v248, v[244:245], off offset:128
	global_load_dword v249, v[244:245], off offset:192
	global_load_dword v250, v[244:245], off offset:256
	global_load_dword v251, v[244:245], off offset:320
	global_load_dword v252, v[244:245], off offset:384
	global_load_dword v253, v[244:245], off offset:448
	s_lshl_b32 s2, s10, 18
	s_add_i32 s2, s2, 0x1e000000
	s_add_u32 s12, s92, s2
	s_addc_u32 s13, s93, 0
	s_add_i32 s2, s11, s10
	s_lshr_b32 s21, s10, 3
	s_add_i32 s2, s2, s21
	s_and_b32 s2, s2, 3
	s_lshl_b32 s2, s2, 19
	s_lshl_b32 s21, s20, 5
	s_add_i32 s2, s2, s21
	s_add_i32 s2, s2, 0x34800000
	s_add_u32 s14, s92, s2
	s_addc_u32 s15, s93, 0
	s_mov_b32 s19, 0
	s_mov_b32 s17, 0
	s_add_i32 m0, s17, s20
	s_nop 0
	global_load_lds_dwordx4 v234, s[12:13]
	s_add_i32 m0, m0, 0x400
	s_nop 0
	global_load_lds_dwordx4 v235, s[12:13]
	s_add_i32 m0, m0, 0x400
	s_nop 0
	global_load_lds_dwordx4 v236, s[12:13]
	s_add_i32 m0, m0, 0x400
	s_nop 0
	global_load_lds_dwordx4 v237, s[12:13]
	s_add_u32 s12, s12, 128
	s_addc_u32 s13, s13, 0
	global_load_dwordx4 v[128:131], v238, s[14:15]
	global_load_dwordx4 v[132:135], v239, s[14:15]
	global_load_dwordx4 v[136:139], v240, s[14:15]
	global_load_dwordx4 v[140:143], v241, s[14:15]
	s_add_u32 s14, s14, 1024
	s_addc_u32 s15, s15, 0
	s_add_i32 s19, s19, 1
	global_load_dwordx4 v[144:147], v238, s[14:15]
	global_load_dwordx4 v[148:151], v239, s[14:15]
	global_load_dwordx4 v[152:155], v240, s[14:15]
	global_load_dwordx4 v[156:159], v241, s[14:15]
	s_add_u32 s14, s14, 1024
	s_addc_u32 s15, s15, 0
	s_add_i32 s19, s19, 1
	s_movk_i32 s17, 0x4000
	s_add_i32 m0, s17, s20
	s_nop 0
	global_load_lds_dwordx4 v234, s[12:13]
	s_add_i32 m0, m0, 0x400
	s_nop 0
	global_load_lds_dwordx4 v235, s[12:13]
	s_add_i32 m0, m0, 0x400
	s_nop 0
	global_load_lds_dwordx4 v236, s[12:13]
	s_add_i32 m0, m0, 0x400
	s_nop 0
	global_load_lds_dwordx4 v237, s[12:13]
	s_add_u32 s12, s12, 128
	s_addc_u32 s13, s13, 0
	global_load_dwordx4 v[160:163], v238, s[14:15]
	global_load_dwordx4 v[164:167], v239, s[14:15]
	global_load_dwordx4 v[168:171], v240, s[14:15]
	global_load_dwordx4 v[172:175], v241, s[14:15]
	s_add_u32 s14, s14, 1024
	s_addc_u32 s15, s15, 0
	s_add_i32 s19, s19, 1
	s_mov_b32 s16, 0
	s_mov_b32 s17, 0x8000

.Lg3_sww0:
	s_cmp_lt_u32 s11, 3
	s_cbranch_scc1 .Lg3_wsamew0
	s_add_i32 s21, s10, s95
	s_cmpk_gt_i32 s21, 0x1ff
	s_cbranch_scc1 .Lg3_wndw0
	s_and_b32 s2, s21, 3
	s_sub_i32 s21, s21, s2
	s_add_i32 s2, s2, s21
	s_lshr_b32 s21, s21, 3
	s_add_i32 s2, s2, s21
	s_and_b32 s2, s2, 3
	s_lshl_b32 s2, s2, 19
	s_lshl_b32 s21, s20, 5
	s_add_i32 s2, s2, s21
	s_add_i32 s2, s2, 0x34800000
	s_add_u32 s14, s92, s2
	s_addc_u32 s15, s93, 0
	s_branch .Lg3_wndw0
.Lg3_wsamew0:
	s_add_i32 s21, s11, 1
	s_add_i32 s2, s21, s10
	s_lshr_b32 s21, s10, 3
	s_add_i32 s2, s2, s21
	s_and_b32 s2, s2, 3
	s_lshl_b32 s2, s2, 19
	s_lshl_b32 s21, s20, 5
	s_add_i32 s2, s2, s21
	s_add_i32 s2, s2, 0x34800000
	s_add_u32 s14, s92, s2
	s_addc_u32 s15, s93, 0

.Lg3_wndw5:
.Lg3_swdw5:
	s_add_i32 s19, s19, 1
	ds_read_b128 v[198:201], v245 offset:0
	ds_read_b128 v[202:205], v245 offset:2048
	ds_read_b128 v[210:213], v245 offset:4096
	ds_read_b128 v[214:217], v245 offset:6144
	ds_read_b128 v[218:221], v245 offset:8192
	ds_read_b128 v[222:225], v245 offset:10240
	ds_read_b128 v[226:229], v245 offset:12288
	ds_read_b128 v[230:233], v245 offset:14336
	s_waitcnt lgkmcnt(4)
	v_mfma_f32_16x16x32_bf16 v[0:3], v[176:179], v[198:201], v[0:3]
	v_mfma_f32_16x16x32_bf16 v[32:35], v[182:185], v[198:201], v[32:35]
	v_mfma_f32_16x16x32_bf16 v[64:67], v[186:189], v[198:201], v[64:67]
	v_mfma_f32_16x16x32_bf16 v[96:99], v[194:197], v[198:201], v[96:99]
	v_mfma_f32_16x16x32_bf16 v[4:7], v[176:179], v[202:205], v[4:7]
	v_mfma_f32_16x16x32_bf16 v[36:39], v[182:185], v[202:205], v[36:39]
	v_mfma_f32_16x16x32_bf16 v[68:71], v[186:189], v[202:205], v[68:71]
	v_mfma_f32_16x16x32_bf16 v[100:103], v[194:197], v[202:205], v[100:103]
	v_mfma_f32_16x16x32_bf16 v[8:11], v[176:179], v[210:213], v[8:11]
	v_mfma_f32_16x16x32_bf16 v[40:43], v[182:185], v[210:213], v[40:43]
	v_mfma_f32_16x16x32_bf16 v[72:75], v[186:189], v[210:213], v[72:75]
	v_mfma_f32_16x16x32_bf16 v[104:107], v[194:197], v[210:213], v[104:107]
	v_mfma_f32_16x16x32_bf16 v[12:15], v[176:179], v[214:217], v[12:15]
	v_mfma_f32_16x16x32_bf16 v[44:47], v[182:185], v[214:217], v[44:47]
	v_mfma_f32_16x16x32_bf16 v[76:79], v[186:189], v[214:217], v[76:79]
	v_mfma_f32_16x16x32_bf16 v[108:111], v[194:197], v[214:217], v[108:111]
	s_waitcnt lgkmcnt(0)
	v_mfma_f32_16x16x32_bf16 v[16:19], v[176:179], v[218:221], v[16:19]
	v_mfma_f32_16x16x32_bf16 v[48:51], v[182:185], v[218:221], v[48:51]
	v_mfma_f32_16x16x32_bf16 v[80:83], v[186:189], v[218:221], v[80:83]
	v_mfma_f32_16x16x32_bf16 v[112:115], v[194:197], v[218:221], v[112:115]
	v_mfma_f32_16x16x32_bf16 v[20:23], v[176:179], v[222:225], v[20:23]
	v_mfma_f32_16x16x32_bf16 v[52:55], v[182:185], v[222:225], v[52:55]
	v_mfma_f32_16x16x32_bf16 v[84:87], v[186:189], v[222:225], v[84:87]
	v_mfma_f32_16x16x32_bf16 v[116:119], v[194:197], v[222:225], v[116:119]
	v_mfma_f32_16x16x32_bf16 v[24:27], v[176:179], v[226:229], v[24:27]
	v_mfma_f32_16x16x32_bf16 v[56:59], v[182:185], v[226:229], v[56:59]
	v_mfma_f32_16x16x32_bf16 v[88:91], v[186:189], v[226:229], v[88:91]
	v_mfma_f32_16x16x32_bf16 v[120:123], v[194:197], v[226:229], v[120:123]
	v_mfma_f32_16x16x32_bf16 v[28:31], v[176:179], v[230:233], v[28:31]
	v_mfma_f32_16x16x32_bf16 v[60:63], v[182:185], v[230:233], v[60:63]
	v_mfma_f32_16x16x32_bf16 v[92:95], v[186:189], v[230:233], v[92:95]
	v_mfma_f32_16x16x32_bf16 v[124:127], v[194:197], v[230:233], v[124:127]
	s_add_i32 s16, s16, 0x4000
	s_cmp_lt_u32 s16, 0xc000
	s_cselect_b32 s16, s16, 0
	s_add_i32 s17, s17, 0x4000
	s_cmp_lt_u32 s17, 0xc000
	s_cselect_b32 s17, s17, 0
	s_add_i32 s18, s18, 1
	s_cmp_lt_u32 s18, 16
	s_cbranch_scc1 .Lg3_loop
	s_nop 7
	s_nop 7
	v_and_b32_e32 v198, 63, v208
	v_lshrrev_b32_e32 v199, 6, v208
	v_and_b32_e32 v200, 15, v198
	v_lshrrev_b32_e32 v201, 4, v198
	s_add_i32 s21, s11, s10
	s_lshr_b32 s2, s10, 3
	s_add_i32 s21, s21, s2
	s_and_b32 s21, s21, 3
	s_lshl_b32 s21, s21, 9
	s_lshl_b32 s2, s10, 18
	s_add_i32 s2, s2, s21
	s_add_i32 s2, s2, 0x26000000
	v_lshlrev_b32_e32 v244, 11, v200
	v_lshl_add_u32 v244, v199, 7, v244
	v_lshl_add_u32 v244, v201, 3, v244
	v_add_u32_e32 v244, s2, v244
	v_mov_b32_e32 v245, s93
	v_add_co_u32_e32 v244, vcc, s92, v244
	s_nop 1
	v_addc_co_u32_e32 v245, vcc, 0, v245, vcc
	v_mul_f32_e32 v0, v246, v0
	v_mul_f32_e32 v1, v246, v1
	v_mul_f32_e32 v2, v246, v2
	v_mul_f32_e32 v3, v246, v3
	v_cvt_pk_bf16_f32 v202, v0, v1
	v_cvt_pk_bf16_f32 v203, v2, v3
	global_store_dwordx2 v[244:245], v[202:203], off offset:0
	v_mul_f32_e32 v32, v246, v32
	v_mul_f32_e32 v33, v246, v33
	v_mul_f32_e32 v34, v246, v34
	v_mul_f32_e32 v35, v246, v35
	v_cvt_pk_bf16_f32 v204, v32, v33
	v_cvt_pk_bf16_f32 v205, v34, v35
	global_store_dwordx2 v[244:245], v[204:205], off offset:32
	v_mul_f32_e32 v64, v246, v64
	v_mul_f32_e32 v65, v246, v65
	v_mul_f32_e32 v66, v246, v66
	v_mul_f32_e32 v67, v246, v67
	v_cvt_pk_bf16_f32 v210, v64, v65
	v_cvt_pk_bf16_f32 v211, v66, v67
	global_store_dwordx2 v[244:245], v[210:211], off offset:64
	v_mul_f32_e32 v96, v246, v96
	v_mul_f32_e32 v97, v246, v97
	v_mul_f32_e32 v98, v246, v98
	v_mul_f32_e32 v99, v246, v99
	v_cvt_pk_bf16_f32 v212, v96, v97
	v_cvt_pk_bf16_f32 v213, v98, v99
	global_store_dwordx2 v[244:245], v[212:213], off offset:96
	v_add_co_u32_e32 v244, vcc, 0x8000, v244
	s_nop 1
	v_addc_co_u32_e32 v245, vcc, 0, v245, vcc
	v_mul_f32_e32 v4, v247, v4
	v_mul_f32_e32 v5, v247, v5
	v_mul_f32_e32 v6, v247, v6
	v_mul_f32_e32 v7, v247, v7
	v_cvt_pk_bf16_f32 v202, v4, v5
	v_cvt_pk_bf16_f32 v203, v6, v7
	global_store_dwordx2 v[244:245], v[202:203], off offset:0
	v_mul_f32_e32 v36, v247, v36
	v_mul_f32_e32 v37, v247, v37
	v_mul_f32_e32 v38, v247, v38
	v_mul_f32_e32 v39, v247, v39
	v_cvt_pk_bf16_f32 v204, v36, v37
	v_cvt_pk_bf16_f32 v205, v38, v39
	global_store_dwordx2 v[244:245], v[204:205], off offset:32
	v_mul_f32_e32 v68, v247, v68
	v_mul_f32_e32 v69, v247, v69
	v_mul_f32_e32 v70, v247, v70
	v_mul_f32_e32 v71, v247, v71
	v_cvt_pk_bf16_f32 v210, v68, v69
	v_cvt_pk_bf16_f32 v211, v70, v71
	global_store_dwordx2 v[244:245], v[210:211], off offset:64
	v_mul_f32_e32 v100, v247, v100
	v_mul_f32_e32 v101, v247, v101
	v_mul_f32_e32 v102, v247, v102
	v_mul_f32_e32 v103, v247, v103
	v_cvt_pk_bf16_f32 v212, v100, v101
	v_cvt_pk_bf16_f32 v213, v102, v103
	global_store_dwordx2 v[244:245], v[212:213], off offset:96
	v_add_co_u32_e32 v244, vcc, 0x8000, v244
	s_nop 1
	v_addc_co_u32_e32 v245, vcc, 0, v245, vcc
	v_mul_f32_e32 v8, v248, v8
	v_mul_f32_e32 v9, v248, v9
	v_mul_f32_e32 v10, v248, v10
	v_mul_f32_e32 v11, v248, v11
	v_cvt_pk_bf16_f32 v202, v8, v9
	v_cvt_pk_bf16_f32 v203, v10, v11
	global_store_dwordx2 v[244:245], v[202:203], off offset:0
	v_mul_f32_e32 v40, v248, v40
	v_mul_f32_e32 v41, v248, v41
	v_mul_f32_e32 v42, v248, v42
	v_mul_f32_e32 v43, v248, v43
	v_cvt_pk_bf16_f32 v204, v40, v41
	v_cvt_pk_bf16_f32 v205, v42, v43
	global_store_dwordx2 v[244:245], v[204:205], off offset:32
	v_mul_f32_e32 v72, v248, v72
	v_mul_f32_e32 v73, v248, v73
	v_mul_f32_e32 v74, v248, v74
	v_mul_f32_e32 v75, v248, v75
	v_cvt_pk_bf16_f32 v210, v72, v73
	v_cvt_pk_bf16_f32 v211, v74, v75
	global_store_dwordx2 v[244:245], v[210:211], off offset:64
	v_mul_f32_e32 v104, v248, v104
	v_mul_f32_e32 v105, v248, v105
	v_mul_f32_e32 v106, v248, v106
	v_mul_f32_e32 v107, v248, v107
	v_cvt_pk_bf16_f32 v212, v104, v105
	v_cvt_pk_bf16_f32 v213, v106, v107
	global_store_dwordx2 v[244:245], v[212:213], off offset:96
	v_add_co_u32_e32 v244, vcc, 0x8000, v244
	s_nop 1
	v_addc_co_u32_e32 v245, vcc, 0, v245, vcc
	v_mul_f32_e32 v12, v249, v12
	v_mul_f32_e32 v13, v249, v13
	v_mul_f32_e32 v14, v249, v14
	v_mul_f32_e32 v15, v249, v15
	v_cvt_pk_bf16_f32 v202, v12, v13
	v_cvt_pk_bf16_f32 v203, v14, v15
	global_store_dwordx2 v[244:245], v[202:203], off offset:0
	v_mul_f32_e32 v44, v249, v44
	v_mul_f32_e32 v45, v249, v45
	v_mul_f32_e32 v46, v249, v46
	v_mul_f32_e32 v47, v249, v47
	v_cvt_pk_bf16_f32 v204, v44, v45
	v_cvt_pk_bf16_f32 v205, v46, v47
	global_store_dwordx2 v[244:245], v[204:205], off offset:32
	v_mul_f32_e32 v76, v249, v76
	v_mul_f32_e32 v77, v249, v77
	v_mul_f32_e32 v78, v249, v78
	v_mul_f32_e32 v79, v249, v79
	v_cvt_pk_bf16_f32 v210, v76, v77
	v_cvt_pk_bf16_f32 v211, v78, v79
	global_store_dwordx2 v[244:245], v[210:211], off offset:64
	v_mul_f32_e32 v108, v249, v108
	v_mul_f32_e32 v109, v249, v109
	v_mul_f32_e32 v110, v249, v110
	v_mul_f32_e32 v111, v249, v111
	v_cvt_pk_bf16_f32 v212, v108, v109
	v_cvt_pk_bf16_f32 v213, v110, v111
	global_store_dwordx2 v[244:245], v[212:213], off offset:96
	v_add_co_u32_e32 v244, vcc, 0x8000, v244
	s_nop 1
	v_addc_co_u32_e32 v245, vcc, 0, v245, vcc
	v_mul_f32_e32 v16, v250, v16
	v_mul_f32_e32 v17, v250, v17
	v_mul_f32_e32 v18, v250, v18
	v_mul_f32_e32 v19, v250, v19
	v_cvt_pk_bf16_f32 v202, v16, v17
	v_cvt_pk_bf16_f32 v203, v18, v19
	global_store_dwordx2 v[244:245], v[202:203], off offset:0
	v_mul_f32_e32 v48, v250, v48
	v_mul_f32_e32 v49, v250, v49
	v_mul_f32_e32 v50, v250, v50
	v_mul_f32_e32 v51, v250, v51
	v_cvt_pk_bf16_f32 v204, v48, v49
	v_cvt_pk_bf16_f32 v205, v50, v51
	global_store_dwordx2 v[244:245], v[204:205], off offset:32
	v_mul_f32_e32 v80, v250, v80
	v_mul_f32_e32 v81, v250, v81
	v_mul_f32_e32 v82, v250, v82
	v_mul_f32_e32 v83, v250, v83
	v_cvt_pk_bf16_f32 v210, v80, v81
	v_cvt_pk_bf16_f32 v211, v82, v83
	global_store_dwordx2 v[244:245], v[210:211], off offset:64
	v_mul_f32_e32 v112, v250, v112
	v_mul_f32_e32 v113, v250, v113
	v_mul_f32_e32 v114, v250, v114
	v_mul_f32_e32 v115, v250, v115
	v_cvt_pk_bf16_f32 v212, v112, v113
	v_cvt_pk_bf16_f32 v213, v114, v115
	global_store_dwordx2 v[244:245], v[212:213], off offset:96
	v_add_co_u32_e32 v244, vcc, 0x8000, v244
	s_nop 1
	v_addc_co_u32_e32 v245, vcc, 0, v245, vcc
	v_mul_f32_e32 v20, v251, v20
	v_mul_f32_e32 v21, v251, v21
	v_mul_f32_e32 v22, v251, v22
	v_mul_f32_e32 v23, v251, v23
	v_cvt_pk_bf16_f32 v202, v20, v21
	v_cvt_pk_bf16_f32 v203, v22, v23
	global_store_dwordx2 v[244:245], v[202:203], off offset:0
	v_mul_f32_e32 v52, v251, v52
	v_mul_f32_e32 v53, v251, v53
	v_mul_f32_e32 v54, v251, v54
	v_mul_f32_e32 v55, v251, v55
	v_cvt_pk_bf16_f32 v204, v52, v53
	v_cvt_pk_bf16_f32 v205, v54, v55
	global_store_dwordx2 v[244:245], v[204:205], off offset:32
	v_mul_f32_e32 v84, v251, v84
	v_mul_f32_e32 v85, v251, v85
	v_mul_f32_e32 v86, v251, v86
	v_mul_f32_e32 v87, v251, v87
	v_cvt_pk_bf16_f32 v210, v84, v85
	v_cvt_pk_bf16_f32 v211, v86, v87
	global_store_dwordx2 v[244:245], v[210:211], off offset:64
	v_mul_f32_e32 v116, v251, v116
	v_mul_f32_e32 v117, v251, v117
	v_mul_f32_e32 v118, v251, v118
	v_mul_f32_e32 v119, v251, v119
	v_cvt_pk_bf16_f32 v212, v116, v117
	v_cvt_pk_bf16_f32 v213, v118, v119
	global_store_dwordx2 v[244:245], v[212:213], off offset:96
	v_add_co_u32_e32 v244, vcc, 0x8000, v244
	s_nop 1
	v_addc_co_u32_e32 v245, vcc, 0, v245, vcc
	v_mul_f32_e32 v24, v252, v24
	v_mul_f32_e32 v25, v252, v25
	v_mul_f32_e32 v26, v252, v26
	v_mul_f32_e32 v27, v252, v27
	v_cvt_pk_bf16_f32 v202, v24, v25
	v_cvt_pk_bf16_f32 v203, v26, v27
	global_store_dwordx2 v[244:245], v[202:203], off offset:0
	v_mul_f32_e32 v56, v252, v56
	v_mul_f32_e32 v57, v252, v57
	v_mul_f32_e32 v58, v252, v58
	v_mul_f32_e32 v59, v252, v59
	v_cvt_pk_bf16_f32 v204, v56, v57
	v_cvt_pk_bf16_f32 v205, v58, v59
	global_store_dwordx2 v[244:245], v[204:205], off offset:32
	v_mul_f32_e32 v88, v252, v88
	v_mul_f32_e32 v89, v252, v89
	v_mul_f32_e32 v90, v252, v90
	v_mul_f32_e32 v91, v252, v91
	v_cvt_pk_bf16_f32 v210, v88, v89
	v_cvt_pk_bf16_f32 v211, v90, v91
	global_store_dwordx2 v[244:245], v[210:211], off offset:64
	v_mul_f32_e32 v120, v252, v120
	v_mul_f32_e32 v121, v252, v121
	v_mul_f32_e32 v122, v252, v122
	v_mul_f32_e32 v123, v252, v123
	v_cvt_pk_bf16_f32 v212, v120, v121
	v_cvt_pk_bf16_f32 v213, v122, v123
	global_store_dwordx2 v[244:245], v[212:213], off offset:96
	v_add_co_u32_e32 v244, vcc, 0x8000, v244
	s_nop 1
	v_addc_co_u32_e32 v245, vcc, 0, v245, vcc
	v_mul_f32_e32 v28, v253, v28
	v_mul_f32_e32 v29, v253, v29
	v_mul_f32_e32 v30, v253, v30
	v_mul_f32_e32 v31, v253, v31
	v_cvt_pk_bf16_f32 v202, v28, v29
	v_cvt_pk_bf16_f32 v203, v30, v31
	global_store_dwordx2 v[244:245], v[202:203], off offset:0
	v_mul_f32_e32 v60, v253, v60
	v_mul_f32_e32 v61, v253, v61
	v_mul_f32_e32 v62, v253, v62
	v_mul_f32_e32 v63, v253, v63
	v_cvt_pk_bf16_f32 v204, v60, v61
	v_cvt_pk_bf16_f32 v205, v62, v63
	global_store_dwordx2 v[244:245], v[204:205], off offset:32
	v_mul_f32_e32 v92, v253, v92
	v_mul_f32_e32 v93, v253, v93
	v_mul_f32_e32 v94, v253, v94
	v_mul_f32_e32 v95, v253, v95
	v_cvt_pk_bf16_f32 v210, v92, v93
	v_cvt_pk_bf16_f32 v211, v94, v95
	global_store_dwordx2 v[244:245], v[210:211], off offset:64
	v_mul_f32_e32 v124, v253, v124
	v_mul_f32_e32 v125, v253, v125
	v_mul_f32_e32 v126, v253, v126
	v_mul_f32_e32 v127, v253, v127
	v_cvt_pk_bf16_f32 v212, v124, v125
	v_cvt_pk_bf16_f32 v213, v126, v127
	global_store_dwordx2 v[244:245], v[212:213], off offset:96
	s_add_i32 s11, s11, 1
	s_cmp_lt_u32 s11, 4
	s_cbranch_scc1 .Lg3_chunk
	s_mov_b32 s11, 0
	s_add_i32 s10, s10, s95
	s_cmpk_gt_i32 s10, 0x1ff
	s_cbranch_scc1 .Lg3_done
	v_and_b32_e32 v244, 15, v208
	v_lshlrev_b32_e32 v244, 2, v244
	s_lshl_b32 s2, s10, 9
	s_add_i32 s2, s2, 0x36c80000
	v_add_u32_e32 v244, s2, v244
	v_mov_b32_e32 v245, s93
	v_add_co_u32_e32 v244, vcc, s92, v244
	s_nop 1
	v_addc_co_u32_e32 v245, vcc, 0, v245, vcc
	global_load_dword v246, v[244:245], off
	global_load_dword v247, v[244:245], off offset:64
	global_load_dword v248, v[244:245], off offset:128
	global_load_dword v249, v[244:245], off offset:192
	global_load_dword v250, v[244:245], off offset:256
	global_load_dword v251, v[244:245], off offset:320
	global_load_dword v252, v[244:245], off offset:384
	global_load_dword v253, v[244:245], off offset:448
	s_branch .Lg3_chunk
